# K-loop heads of the three GEMM loops aligned to 64 bytes
# baseline (speedup 1.0000x reference)
.LBB0_231:
	s_ashr_i32 s77, s76, 31
	s_lshl_b64 s[66:67], s[76:77], 19
	s_add_u32 s80, s12, s66
	s_addc_u32 s81, s13, s67
	s_and_b64 s[66:67], s[78:79], exec
	s_cselect_b32 s66, s81, s85
	s_cselect_b32 s67, s80, s84
	s_ashr_i32 s75, s74, 31
	s_lshl_b64 s[68:69], s[74:75], 19
	s_add_u32 s82, s5, s68
	s_addc_u32 s83, s20, s69
	s_and_b64 s[68:69], s[78:79], exec
	s_cselect_b32 s68, s83, s87
	s_cselect_b32 s69, s82, s86
	s_add_u32 s84, s84, 0x40080
	s_addc_u32 s85, s85, 0
	s_add_u32 s75, s86, 0x100
	v_mov_b64_e32 v[0:1], 0
	s_addc_u32 s77, s87, 0
	s_mov_b32 s90, -2
	v_mov_b64_e32 v[2:3], 0
	v_mov_b64_e32 v[4:5], 0
	v_mov_b64_e32 v[6:7], 0
	v_mov_b64_e32 v[8:9], 0
	v_mov_b64_e32 v[10:11], 0
	v_mov_b64_e32 v[12:13], 0
	v_mov_b64_e32 v[14:15], 0
	v_mov_b64_e32 v[16:17], 0
	v_mov_b64_e32 v[18:19], 0
	v_mov_b64_e32 v[20:21], 0
	v_mov_b64_e32 v[22:23], 0
	v_mov_b64_e32 v[24:25], 0
	v_mov_b64_e32 v[26:27], 0
	v_mov_b64_e32 v[28:29], 0
	v_mov_b64_e32 v[30:31], 0
	v_mov_b64_e32 v[32:33], 0
	v_mov_b64_e32 v[34:35], 0
	v_mov_b64_e32 v[36:37], 0
	v_mov_b64_e32 v[38:39], 0
	v_mov_b64_e32 v[40:41], 0
	v_mov_b64_e32 v[42:43], 0
	v_mov_b64_e32 v[44:45], 0
	v_mov_b64_e32 v[46:47], 0
	v_mov_b64_e32 v[48:49], 0
	v_mov_b64_e32 v[50:51], 0
	v_mov_b64_e32 v[52:53], 0
	v_mov_b64_e32 v[54:55], 0
	v_mov_b64_e32 v[56:57], 0
	v_mov_b64_e32 v[58:59], 0
	v_mov_b64_e32 v[60:61], 0
	v_mov_b64_e32 v[62:63], 0
	v_mov_b64_e32 v[64:65], 0
	v_mov_b64_e32 v[66:67], 0
	v_mov_b64_e32 v[68:69], 0
	v_mov_b64_e32 v[70:71], 0
	v_mov_b64_e32 v[72:73], 0
	v_mov_b64_e32 v[74:75], 0
	v_mov_b64_e32 v[76:77], 0
	v_mov_b64_e32 v[78:79], 0
	v_mov_b64_e32 v[80:81], 0
	v_mov_b64_e32 v[82:83], 0
	v_mov_b64_e32 v[84:85], 0
	v_mov_b64_e32 v[86:87], 0
	v_mov_b64_e32 v[88:89], 0
	v_mov_b64_e32 v[90:91], 0
	v_mov_b64_e32 v[92:93], 0
	v_mov_b64_e32 v[94:95], 0
	v_mov_b64_e32 v[100:101], 0
	v_mov_b64_e32 v[102:103], 0
	v_mov_b64_e32 v[104:105], 0
	v_mov_b64_e32 v[106:107], 0
	v_mov_b64_e32 v[108:109], 0
	v_mov_b64_e32 v[110:111], 0
	v_mov_b64_e32 v[112:113], 0
	v_mov_b64_e32 v[114:115], 0
	v_mov_b64_e32 v[116:117], 0
	v_mov_b64_e32 v[118:119], 0
	v_mov_b64_e32 v[120:121], 0
	v_mov_b64_e32 v[122:123], 0
	v_mov_b64_e32 v[124:125], 0
	v_mov_b64_e32 v[126:127], 0
	v_mov_b64_e32 v[128:129], 0
	v_mov_b64_e32 v[130:131], 0
	s_waitcnt vmcnt(0)
	.p2align	6

.LBB0_309:
	s_add_u32 s84, s84, 0x80
	s_addc_u32 s85, s85, 0
	s_add_u32 s26, s86, 0x100
	v_mov_b64_e32 v[0:1], 0
	s_addc_u32 s27, s87, 0
	s_mov_b32 s0, 0
	s_waitcnt lgkmcnt(0)
	v_mov_b64_e32 v[2:3], 0
	v_mov_b64_e32 v[4:5], 0
	v_mov_b64_e32 v[6:7], 0
	v_mov_b64_e32 v[8:9], 0
	v_mov_b64_e32 v[10:11], 0
	v_mov_b64_e32 v[12:13], 0
	v_mov_b64_e32 v[14:15], 0
	v_mov_b64_e32 v[16:17], 0
	v_mov_b64_e32 v[18:19], 0
	v_mov_b64_e32 v[20:21], 0
	v_mov_b64_e32 v[22:23], 0
	v_mov_b64_e32 v[24:25], 0
	v_mov_b64_e32 v[26:27], 0
	v_mov_b64_e32 v[28:29], 0
	v_mov_b64_e32 v[30:31], 0
	v_mov_b64_e32 v[32:33], 0
	v_mov_b64_e32 v[34:35], 0
	v_mov_b64_e32 v[36:37], 0
	v_mov_b64_e32 v[38:39], 0
	v_mov_b64_e32 v[40:41], 0
	v_mov_b64_e32 v[42:43], 0
	v_mov_b64_e32 v[44:45], 0
	v_mov_b64_e32 v[46:47], 0
	v_mov_b64_e32 v[48:49], 0
	v_mov_b64_e32 v[50:51], 0
	v_mov_b64_e32 v[52:53], 0
	v_mov_b64_e32 v[54:55], 0
	v_mov_b64_e32 v[56:57], 0
	v_mov_b64_e32 v[58:59], 0
	v_mov_b64_e32 v[60:61], 0
	v_mov_b64_e32 v[62:63], 0
	v_mov_b64_e32 v[64:65], 0
	v_mov_b64_e32 v[66:67], 0
	v_mov_b64_e32 v[68:69], 0
	v_mov_b64_e32 v[70:71], 0
	v_mov_b64_e32 v[72:73], 0
	v_mov_b64_e32 v[74:75], 0
	v_mov_b64_e32 v[76:77], 0
	v_mov_b64_e32 v[78:79], 0
	v_mov_b64_e32 v[80:81], 0
	v_mov_b64_e32 v[82:83], 0
	v_mov_b64_e32 v[84:85], 0
	v_mov_b64_e32 v[86:87], 0
	v_mov_b64_e32 v[88:89], 0
	v_mov_b64_e32 v[90:91], 0
	v_mov_b64_e32 v[92:93], 0
	v_mov_b64_e32 v[94:95], 0
	v_mov_b64_e32 v[100:101], 0
	v_mov_b64_e32 v[102:103], 0
	v_mov_b64_e32 v[104:105], 0
	v_mov_b64_e32 v[106:107], 0
	v_mov_b64_e32 v[108:109], 0
	v_mov_b64_e32 v[110:111], 0
	v_mov_b64_e32 v[112:113], 0
	v_mov_b64_e32 v[114:115], 0
	v_mov_b64_e32 v[116:117], 0
	v_mov_b64_e32 v[118:119], 0
	v_mov_b64_e32 v[120:121], 0
	v_mov_b64_e32 v[122:123], 0
	v_mov_b64_e32 v[124:125], 0
	v_mov_b64_e32 v[126:127], 0
	v_mov_b64_e32 v[128:129], 0
	v_mov_b64_e32 v[130:131], 0
	s_waitcnt vmcnt(0)
	.p2align	6

.LBB0_345:
	s_ashr_i32 s71, s70, 31
	s_lshl_b64 s[56:57], s[70:71], 19
	s_add_u32 s74, s12, s56
	s_addc_u32 s75, s13, s57
	s_and_b64 s[56:57], s[72:73], exec
	s_cselect_b32 s27, s75, s79
	s_cselect_b32 s42, s74, s78
	s_ashr_i32 s69, s68, 31
	s_lshl_b64 s[56:57], s[68:69], 19
	s_add_u32 s76, s4, s56
	s_addc_u32 s77, s5, s57
	s_and_b64 s[56:57], s[72:73], exec
	s_cselect_b32 s56, s77, s81
	s_cselect_b32 s57, s76, s80
	s_add_u32 s78, s78, 0x40080
	s_addc_u32 s79, s79, 0
	s_add_u32 s69, s80, 0x100
	v_mov_b64_e32 v[0:1], 0
	s_addc_u32 s71, s81, 0
	s_mov_b32 s84, -2
	v_mov_b64_e32 v[2:3], 0
	v_mov_b64_e32 v[4:5], 0
	v_mov_b64_e32 v[6:7], 0
	v_mov_b64_e32 v[8:9], 0
	v_mov_b64_e32 v[10:11], 0
	v_mov_b64_e32 v[12:13], 0
	v_mov_b64_e32 v[14:15], 0
	v_mov_b64_e32 v[16:17], 0
	v_mov_b64_e32 v[18:19], 0
	v_mov_b64_e32 v[20:21], 0
	v_mov_b64_e32 v[22:23], 0
	v_mov_b64_e32 v[24:25], 0
	v_mov_b64_e32 v[26:27], 0
	v_mov_b64_e32 v[28:29], 0
	v_mov_b64_e32 v[30:31], 0
	v_mov_b64_e32 v[32:33], 0
	v_mov_b64_e32 v[34:35], 0
	v_mov_b64_e32 v[36:37], 0
	v_mov_b64_e32 v[38:39], 0
	v_mov_b64_e32 v[40:41], 0
	v_mov_b64_e32 v[42:43], 0
	v_mov_b64_e32 v[44:45], 0
	v_mov_b64_e32 v[46:47], 0
	v_mov_b64_e32 v[48:49], 0
	v_mov_b64_e32 v[50:51], 0
	v_mov_b64_e32 v[52:53], 0
	v_mov_b64_e32 v[54:55], 0
	v_mov_b64_e32 v[56:57], 0
	v_mov_b64_e32 v[58:59], 0
	v_mov_b64_e32 v[60:61], 0
	v_mov_b64_e32 v[62:63], 0
	v_mov_b64_e32 v[64:65], 0
	v_mov_b64_e32 v[66:67], 0
	v_mov_b64_e32 v[68:69], 0
	v_mov_b64_e32 v[70:71], 0
	v_mov_b64_e32 v[72:73], 0
	v_mov_b64_e32 v[74:75], 0
	v_mov_b64_e32 v[76:77], 0
	v_mov_b64_e32 v[78:79], 0
	v_mov_b64_e32 v[80:81], 0
	v_mov_b64_e32 v[82:83], 0
	v_mov_b64_e32 v[84:85], 0
	v_mov_b64_e32 v[86:87], 0
	v_mov_b64_e32 v[88:89], 0
	v_mov_b64_e32 v[90:91], 0
	v_mov_b64_e32 v[92:93], 0
	v_mov_b64_e32 v[94:95], 0
	v_mov_b64_e32 v[100:101], 0
	v_mov_b64_e32 v[102:103], 0
	v_mov_b64_e32 v[104:105], 0
	v_mov_b64_e32 v[106:107], 0
	v_mov_b64_e32 v[108:109], 0
	v_mov_b64_e32 v[110:111], 0
	v_mov_b64_e32 v[112:113], 0
	v_mov_b64_e32 v[114:115], 0
	v_mov_b64_e32 v[116:117], 0
	v_mov_b64_e32 v[118:119], 0
	v_mov_b64_e32 v[120:121], 0
	v_mov_b64_e32 v[122:123], 0
	v_mov_b64_e32 v[124:125], 0
	v_mov_b64_e32 v[126:127], 0
	v_mov_b64_e32 v[128:129], 0
	v_mov_b64_e32 v[130:131], 0
	s_waitcnt vmcnt(0)
	.p2align	6
